# stacked version plus batched mode-7 (merge GEMM) epilogue: gate loads pipelined three batches deep with counted vmcnt
# baseline (speedup 1.0000x reference)
; DEVI float bf_lo(unsigned u) { return __uint_as_float(u << 16); }
; DEVI float bf_hi(unsigned u) { return __uint_as_float(u & 0xffff0000u); }
; DEVI float sigmoidf_(float x) { return 1.f / (1.f + __expf(-x)); }
; DEVI u32x4 pack8(f32x4 a, f32x4 b) { u32x4 o; o.x = cvt_pk_bf16(a[0], a[1]); o.y = cvt_pk_bf16(a[2], a[3]); o.z = cvt_pk_bf16(b[0], b[1]); o.w = cvt_pk_bf16(b[2], b[3]); return o; }
; DEVI void gemm_epi(const GJob& jb, int row, int col, f32x4 v0, f32x4 v1) {
;   const int mode = jb.mode;
;   if (mode == 0) { *(u32x4*)((bf16_t*)jb.out + (size_t)row * jb.ldo + col) = pack8(v0, v1); }
;   else if (mode == 1) { float* p = (float*)jb.out + (size_t)row * jb.ldo + col; *(f32x4*)p = v0; *(f32x4*)(p + 4) = v1; }
;   else if (mode == 2) { f32x4 s0, s1; for (int i = 0; i < 4; ++i) { s0[i] = sigmoidf_(v0[i]); s1[i] = sigmoidf_(v1[i]); } *(u32x4*)((bf16_t*)jb.out + (size_t)row * jb.ldo + col) = pack8(s0, s1); }
;   else if (mode == 7) {
;     const u32x4 g = *(const u32x4*)((const bf16_t*)jb.aux + (size_t)row * NGATE + 2 * 2048 + col);
;     const f32x4 g0 = {bf_lo(g.x), bf_hi(g.x), bf_lo(g.y), bf_hi(g.y)}, g1 = {bf_lo(g.z), bf_hi(g.z), bf_lo(g.w), bf_hi(g.w)};
;     *(u32x4*)((bf16_t*)jb.out + (size_t)row * 2048 + col) = pack8(g0 * v0, g1 * v1);
; DEVI void gemm_tile(const GJob& jb, int brow, int bcol, unsigned char* shm_) {
;     ...
;   for (int ai = 0; ai < 2; ++ai)
; #pragma unroll
;     for (int m = 0; m < 4; ++m)
; #pragma unroll
;       for (int bj = 0; bj < 2; ++bj)
;         gemm_epi(jb, brow + ai * HALF + wr * 64 + m * 16 + fr, bcol + bj * HALF + wc * 32 + fq * 8, acc[ai][bj][m][0], acc[ai][bj][m][1]);
.LBB0_424:
	s_setprio 0
	v_or_b32_e32 v0, s43, v159
	v_add_u32_e32 v132, s47, v0
	v_or_b32_e32 v0, s12, v158
	v_ashrrev_i32_e32 v133, 31, v132
	v_or_b32_e32 v130, s68, v0
	s_cmp_eq_u32 s71, 6
	s_cbranch_scc1 .Lepi6
	s_cmp_eq_u32 s71, 7
	s_cbranch_scc1 .Lepi7
	v_mad_i64_i32 v[136:137], s[0:1], v132, s33, 0
	v_lshlrev_b64 v[134:135], 12, v[132:133]
	s_mov_b64 s[12:13], -1
	s_mov_b64 s[10:11], 0
	s_cmp_lt_i32 s71, 2
	s_mov_b64 s[8:9], 0
	s_cbranch_scc1 .LBB0_433
	s_cmp_gt_i32 s71, 6
	s_cbranch_scc0 .LBB0_429
	s_cmp_eq_u32 s71, 7
	s_mov_b64 s[8:9], -1
	s_cbranch_scc0 .LBB0_428
	v_ashrrev_i32_e32 v131, 31, v130
	v_lshl_add_u64 v[138:139], s[94:95], 0, v[136:137]
	v_lshlrev_b64 v[142:143], 1, v[130:131]
	v_lshl_add_u64 v[138:139], v[138:139], 0, v[142:143]
	v_add_co_u32_e32 v138, vcc, 0x2000, v138
	v_lshl_add_u64 v[144:145], s[90:91], 0, v[134:135]
	s_nop 0
	v_addc_co_u32_e32 v139, vcc, 0, v139, vcc
	global_load_dwordx4 v[138:141], v[138:139], off
	v_lshl_add_u64 v[142:143], v[144:145], 0, v[142:143]
	s_mov_b64 s[8:9], 0
	s_waitcnt vmcnt(0) lgkmcnt(0)
	v_lshlrev_b32_e32 v144, 16, v138
	v_and_b32_e32 v145, 0xffff0000, v138
	v_lshlrev_b32_e32 v138, 16, v139
	v_and_b32_e32 v139, 0xffff0000, v139
	v_lshlrev_b32_e32 v146, 16, v140
	v_and_b32_e32 v147, 0xffff0000, v140
	v_lshlrev_b32_e32 v140, 16, v141
	v_and_b32_e32 v141, 0xffff0000, v141
	v_pk_mul_f32 v[148:149], v[128:129], v[138:139]
	v_pk_mul_f32 v[138:139], v[126:127], v[144:145]
	v_pk_mul_f32 v[144:145], v[124:125], v[140:141]
	v_pk_mul_f32 v[140:141], v[122:123], v[146:147]
	v_cvt_pk_bf16_f32 v138, v138, v139
	v_cvt_pk_bf16_f32 v139, v148, v149
	s_nop 0
	v_cvt_pk_bf16_f32 v140, v140, v141
	v_cvt_pk_bf16_f32 v141, v144, v145
	global_store_dwordx4 v[142:143], v[138:141], off
